# residual-add GEMM epilogues (out-proj, down-proj): 16 loads in flight per batch with counted vmcnt instead of a load-wait-add-store ladder; -15% wave cycles in P4
# speedup vs baseline: 1.0048x; 1.0048x over previous
.LBB0_567:
	v_lshl_add_u32 v152, s48, 8, v142
	v_lshl_or_b32 v154, s81, 8, v144
	v_ashrrev_i32_e32 v153, 31, v152
	v_ashrrev_i32_e32 v155, 31, v154
	v_lshlrev_b64 v[140:141], 11, v[152:153]
	v_lshl_add_u64 v[140:141], v[140:141], 0, v[154:155]
	v_lshlrev_b64 v[140:141], 2, v[140:141]
	s_andn2_b64 vcc, exec, s[4:5]
	s_mov_b64 s[4:5], -1
	v_mov_b32_e32 v226, v140
	v_add_u32_e32 v227, 0x20000, v140
	v_add_u32_e32 v228, 0x40000, v140
	v_add_u32_e32 v229, 0x60000, v140
	v_add_u32_e32 v230, 0x100000, v140
	v_add_u32_e32 v231, 0x120000, v140
	v_add_u32_e32 v232, 0x140000, v140
	v_add_u32_e32 v233, 0x160000, v140
	global_load_dwordx4 v[160:163], v226, s[36:37] offset:0
	global_load_dwordx4 v[164:167], v226, s[36:37] offset:64
	global_load_dwordx4 v[168:171], v226, s[36:37] offset:512
	global_load_dwordx4 v[172:175], v226, s[36:37] offset:576
	global_load_dwordx4 v[176:179], v227, s[36:37] offset:0
	global_load_dwordx4 v[180:183], v227, s[36:37] offset:64
	global_load_dwordx4 v[184:187], v227, s[36:37] offset:512
	global_load_dwordx4 v[188:191], v227, s[36:37] offset:576
	global_load_dwordx4 v[192:195], v228, s[36:37] offset:0
	global_load_dwordx4 v[196:199], v228, s[36:37] offset:64
	global_load_dwordx4 v[200:203], v228, s[36:37] offset:512
	global_load_dwordx4 v[206:209], v228, s[36:37] offset:576
	global_load_dwordx4 v[210:213], v229, s[36:37] offset:0
	global_load_dwordx4 v[214:217], v229, s[36:37] offset:64
	global_load_dwordx4 v[218:221], v229, s[36:37] offset:512
	global_load_dwordx4 v[222:225], v229, s[36:37] offset:576
	s_waitcnt vmcnt(15)
	v_pk_add_f32 v[124:125], v[124:125], v[160:161]
	v_pk_add_f32 v[126:127], v[126:127], v[162:163]
	global_store_dwordx4 v226, v[124:127], s[26:27] offset:0
	s_waitcnt vmcnt(15)
	v_pk_add_f32 v[120:121], v[120:121], v[164:165]
	v_pk_add_f32 v[122:123], v[122:123], v[166:167]
	global_store_dwordx4 v226, v[120:123], s[26:27] offset:64
	s_waitcnt vmcnt(15)
	v_pk_add_f32 v[116:117], v[116:117], v[168:169]
	v_pk_add_f32 v[118:119], v[118:119], v[170:171]
	global_store_dwordx4 v226, v[116:119], s[26:27] offset:512
	s_waitcnt vmcnt(15)
	v_pk_add_f32 v[104:105], v[104:105], v[172:173]
	v_pk_add_f32 v[106:107], v[106:107], v[174:175]
	global_store_dwordx4 v226, v[104:107], s[26:27] offset:576
	s_waitcnt vmcnt(15)
	v_pk_add_f32 v[112:113], v[112:113], v[176:177]
	v_pk_add_f32 v[114:115], v[114:115], v[178:179]
	global_store_dwordx4 v227, v[112:115], s[26:27] offset:0
	s_waitcnt vmcnt(15)
	v_pk_add_f32 v[108:109], v[108:109], v[180:181]
	v_pk_add_f32 v[110:111], v[110:111], v[182:183]
	global_store_dwordx4 v227, v[108:111], s[26:27] offset:64
	s_waitcnt vmcnt(15)
	v_pk_add_f32 v[100:101], v[100:101], v[184:185]
	v_pk_add_f32 v[102:103], v[102:103], v[186:187]
	global_store_dwordx4 v227, v[100:103], s[26:27] offset:512
	s_waitcnt vmcnt(15)
	v_pk_add_f32 v[88:89], v[88:89], v[188:189]
	v_pk_add_f32 v[90:91], v[90:91], v[190:191]
	global_store_dwordx4 v227, v[88:91], s[26:27] offset:576
	s_waitcnt vmcnt(15)
	v_pk_add_f32 v[96:97], v[96:97], v[192:193]
	v_pk_add_f32 v[98:99], v[98:99], v[194:195]
	global_store_dwordx4 v228, v[96:99], s[26:27] offset:0
	s_waitcnt vmcnt(15)
	v_pk_add_f32 v[92:93], v[92:93], v[196:197]
	v_pk_add_f32 v[94:95], v[94:95], v[198:199]
	global_store_dwordx4 v228, v[92:95], s[26:27] offset:64
	s_waitcnt vmcnt(15)
	v_pk_add_f32 v[84:85], v[84:85], v[200:201]
	v_pk_add_f32 v[86:87], v[86:87], v[202:203]
	global_store_dwordx4 v228, v[84:87], s[26:27] offset:512
	s_waitcnt vmcnt(15)
	v_pk_add_f32 v[72:73], v[72:73], v[206:207]
	v_pk_add_f32 v[74:75], v[74:75], v[208:209]
	global_store_dwordx4 v228, v[72:75], s[26:27] offset:576
	s_waitcnt vmcnt(15)
	v_pk_add_f32 v[80:81], v[80:81], v[210:211]
	v_pk_add_f32 v[82:83], v[82:83], v[212:213]
	global_store_dwordx4 v229, v[80:83], s[26:27] offset:0
	s_waitcnt vmcnt(15)
	v_pk_add_f32 v[76:77], v[76:77], v[214:215]
	v_pk_add_f32 v[78:79], v[78:79], v[216:217]
	global_store_dwordx4 v229, v[76:79], s[26:27] offset:64
	s_waitcnt vmcnt(15)
	v_pk_add_f32 v[68:69], v[68:69], v[218:219]
	v_pk_add_f32 v[70:71], v[70:71], v[220:221]
	global_store_dwordx4 v229, v[68:71], s[26:27] offset:512
	s_waitcnt vmcnt(15)
	v_pk_add_f32 v[64:65], v[64:65], v[222:223]
	v_pk_add_f32 v[66:67], v[66:67], v[224:225]
	global_store_dwordx4 v229, v[64:67], s[26:27] offset:576
	global_load_dwordx4 v[160:163], v230, s[36:37] offset:0
	global_load_dwordx4 v[164:167], v230, s[36:37] offset:64
	global_load_dwordx4 v[168:171], v230, s[36:37] offset:512
	global_load_dwordx4 v[172:175], v230, s[36:37] offset:576
	global_load_dwordx4 v[176:179], v231, s[36:37] offset:0
	global_load_dwordx4 v[180:183], v231, s[36:37] offset:64
	global_load_dwordx4 v[184:187], v231, s[36:37] offset:512
	global_load_dwordx4 v[188:191], v231, s[36:37] offset:576
	global_load_dwordx4 v[192:195], v232, s[36:37] offset:0
	global_load_dwordx4 v[196:199], v232, s[36:37] offset:64
	global_load_dwordx4 v[200:203], v232, s[36:37] offset:512
	global_load_dwordx4 v[206:209], v232, s[36:37] offset:576
	global_load_dwordx4 v[210:213], v233, s[36:37] offset:0
	global_load_dwordx4 v[214:217], v233, s[36:37] offset:64
	global_load_dwordx4 v[218:221], v233, s[36:37] offset:512
	global_load_dwordx4 v[222:225], v233, s[36:37] offset:576
	s_waitcnt vmcnt(15)
	v_pk_add_f32 v[60:61], v[60:61], v[160:161]
	v_pk_add_f32 v[62:63], v[62:63], v[162:163]
	global_store_dwordx4 v230, v[60:63], s[26:27] offset:0
	s_waitcnt vmcnt(15)
	v_pk_add_f32 v[56:57], v[56:57], v[164:165]
	v_pk_add_f32 v[58:59], v[58:59], v[166:167]
	global_store_dwordx4 v230, v[56:59], s[26:27] offset:64
	s_waitcnt vmcnt(15)
	v_pk_add_f32 v[52:53], v[52:53], v[168:169]
	v_pk_add_f32 v[54:55], v[54:55], v[170:171]
	global_store_dwordx4 v230, v[52:55], s[26:27] offset:512
	s_waitcnt vmcnt(15)
	v_pk_add_f32 v[40:41], v[40:41], v[172:173]
	v_pk_add_f32 v[42:43], v[42:43], v[174:175]
	global_store_dwordx4 v230, v[40:43], s[26:27] offset:576
	s_waitcnt vmcnt(15)
	v_pk_add_f32 v[48:49], v[48:49], v[176:177]
	v_pk_add_f32 v[50:51], v[50:51], v[178:179]
	global_store_dwordx4 v231, v[48:51], s[26:27] offset:0
	s_waitcnt vmcnt(15)
	v_pk_add_f32 v[44:45], v[44:45], v[180:181]
	v_pk_add_f32 v[46:47], v[46:47], v[182:183]
	global_store_dwordx4 v231, v[44:47], s[26:27] offset:64
	s_waitcnt vmcnt(15)
	v_pk_add_f32 v[36:37], v[36:37], v[184:185]
	v_pk_add_f32 v[38:39], v[38:39], v[186:187]
	global_store_dwordx4 v231, v[36:39], s[26:27] offset:512
	s_waitcnt vmcnt(15)
	v_pk_add_f32 v[24:25], v[24:25], v[188:189]
	v_pk_add_f32 v[26:27], v[26:27], v[190:191]
	global_store_dwordx4 v231, v[24:27], s[26:27] offset:576
	s_waitcnt vmcnt(15)
	v_pk_add_f32 v[32:33], v[32:33], v[192:193]
	v_pk_add_f32 v[34:35], v[34:35], v[194:195]
	global_store_dwordx4 v232, v[32:35], s[26:27] offset:0
	s_waitcnt vmcnt(15)
	v_pk_add_f32 v[28:29], v[28:29], v[196:197]
	v_pk_add_f32 v[30:31], v[30:31], v[198:199]
	global_store_dwordx4 v232, v[28:31], s[26:27] offset:64
	s_waitcnt vmcnt(15)
	v_pk_add_f32 v[20:21], v[20:21], v[200:201]
	v_pk_add_f32 v[22:23], v[22:23], v[202:203]
	global_store_dwordx4 v232, v[20:23], s[26:27] offset:512
	s_waitcnt vmcnt(15)
	v_pk_add_f32 v[8:9], v[8:9], v[206:207]
	v_pk_add_f32 v[10:11], v[10:11], v[208:209]
	global_store_dwordx4 v232, v[8:11], s[26:27] offset:576
	s_waitcnt vmcnt(15)
	v_pk_add_f32 v[16:17], v[16:17], v[210:211]
	v_pk_add_f32 v[18:19], v[18:19], v[212:213]
	global_store_dwordx4 v233, v[16:19], s[26:27] offset:0
	s_waitcnt vmcnt(15)
	v_pk_add_f32 v[12:13], v[12:13], v[214:215]
	v_pk_add_f32 v[14:15], v[14:15], v[216:217]
	global_store_dwordx4 v233, v[12:15], s[26:27] offset:64
	s_waitcnt vmcnt(15)
	v_pk_add_f32 v[4:5], v[4:5], v[218:219]
	v_pk_add_f32 v[6:7], v[6:7], v[220:221]
	global_store_dwordx4 v233, v[4:7], s[26:27] offset:512
	s_waitcnt vmcnt(15)
	v_pk_add_f32 v[0:1], v[0:1], v[222:223]
	v_pk_add_f32 v[2:3], v[2:3], v[224:225]
	global_store_dwordx4 v233, v[0:3], s[26:27] offset:576
	s_cbranch_vccnz .LBB0_556
	s_andn2_b64 vcc, exec, s[6:7]
	s_cbranch_vccnz .LBB0_555
	s_barrier
	s_branch .LBB0_555

.LBB0_779:
	v_lshl_add_u32 v152, s68, 8, v142
	v_lshl_or_b32 v154, s69, 8, v144
	v_ashrrev_i32_e32 v153, 31, v152
	v_ashrrev_i32_e32 v155, 31, v154
	v_lshlrev_b64 v[140:141], 11, v[152:153]
	v_lshl_add_u64 v[140:141], v[140:141], 0, v[154:155]
	v_lshlrev_b64 v[140:141], 2, v[140:141]
	s_and_b64 vcc, exec, s[4:5]
	s_mov_b64 s[4:5], -1
	v_mov_b32_e32 v226, v140
	v_add_u32_e32 v227, 0x20000, v140
	v_add_u32_e32 v228, 0x40000, v140
	v_add_u32_e32 v229, 0x60000, v140
	v_add_u32_e32 v230, 0x100000, v140
	v_add_u32_e32 v231, 0x120000, v140
	v_add_u32_e32 v232, 0x140000, v140
	v_add_u32_e32 v233, 0x160000, v140
	global_load_dwordx4 v[160:163], v226, s[26:27] offset:0
	global_load_dwordx4 v[164:167], v226, s[26:27] offset:64
	global_load_dwordx4 v[168:171], v226, s[26:27] offset:512
	global_load_dwordx4 v[172:175], v226, s[26:27] offset:576
	global_load_dwordx4 v[176:179], v227, s[26:27] offset:0
	global_load_dwordx4 v[180:183], v227, s[26:27] offset:64
	global_load_dwordx4 v[184:187], v227, s[26:27] offset:512
	global_load_dwordx4 v[188:191], v227, s[26:27] offset:576
	global_load_dwordx4 v[192:195], v228, s[26:27] offset:0
	global_load_dwordx4 v[196:199], v228, s[26:27] offset:64
	global_load_dwordx4 v[200:203], v228, s[26:27] offset:512
	global_load_dwordx4 v[206:209], v228, s[26:27] offset:576
	global_load_dwordx4 v[210:213], v229, s[26:27] offset:0
	global_load_dwordx4 v[214:217], v229, s[26:27] offset:64
	global_load_dwordx4 v[218:221], v229, s[26:27] offset:512
	global_load_dwordx4 v[222:225], v229, s[26:27] offset:576
	s_waitcnt vmcnt(15)
	v_pk_add_f32 v[124:125], v[124:125], v[160:161]
	v_pk_add_f32 v[126:127], v[126:127], v[162:163]
	global_store_dwordx4 v226, v[124:127], s[58:59] offset:0
	s_waitcnt vmcnt(15)
	v_pk_add_f32 v[120:121], v[120:121], v[164:165]
	v_pk_add_f32 v[122:123], v[122:123], v[166:167]
	global_store_dwordx4 v226, v[120:123], s[58:59] offset:64
	s_waitcnt vmcnt(15)
	v_pk_add_f32 v[116:117], v[116:117], v[168:169]
	v_pk_add_f32 v[118:119], v[118:119], v[170:171]
	global_store_dwordx4 v226, v[116:119], s[58:59] offset:512
	s_waitcnt vmcnt(15)
	v_pk_add_f32 v[104:105], v[104:105], v[172:173]
	v_pk_add_f32 v[106:107], v[106:107], v[174:175]
	global_store_dwordx4 v226, v[104:107], s[58:59] offset:576
	s_waitcnt vmcnt(15)
	v_pk_add_f32 v[112:113], v[112:113], v[176:177]
	v_pk_add_f32 v[114:115], v[114:115], v[178:179]
	global_store_dwordx4 v227, v[112:115], s[58:59] offset:0
	s_waitcnt vmcnt(15)
	v_pk_add_f32 v[108:109], v[108:109], v[180:181]
	v_pk_add_f32 v[110:111], v[110:111], v[182:183]
	global_store_dwordx4 v227, v[108:111], s[58:59] offset:64
	s_waitcnt vmcnt(15)
	v_pk_add_f32 v[100:101], v[100:101], v[184:185]
	v_pk_add_f32 v[102:103], v[102:103], v[186:187]
	global_store_dwordx4 v227, v[100:103], s[58:59] offset:512
	s_waitcnt vmcnt(15)
	v_pk_add_f32 v[88:89], v[88:89], v[188:189]
	v_pk_add_f32 v[90:91], v[90:91], v[190:191]
	global_store_dwordx4 v227, v[88:91], s[58:59] offset:576
	s_waitcnt vmcnt(15)
	v_pk_add_f32 v[96:97], v[96:97], v[192:193]
	v_pk_add_f32 v[98:99], v[98:99], v[194:195]
	global_store_dwordx4 v228, v[96:99], s[58:59] offset:0
	s_waitcnt vmcnt(15)
	v_pk_add_f32 v[92:93], v[92:93], v[196:197]
	v_pk_add_f32 v[94:95], v[94:95], v[198:199]
	global_store_dwordx4 v228, v[92:95], s[58:59] offset:64
	s_waitcnt vmcnt(15)
	v_pk_add_f32 v[84:85], v[84:85], v[200:201]
	v_pk_add_f32 v[86:87], v[86:87], v[202:203]
	global_store_dwordx4 v228, v[84:87], s[58:59] offset:512
	s_waitcnt vmcnt(15)
	v_pk_add_f32 v[72:73], v[72:73], v[206:207]
	v_pk_add_f32 v[74:75], v[74:75], v[208:209]
	global_store_dwordx4 v228, v[72:75], s[58:59] offset:576
	s_waitcnt vmcnt(15)
	v_pk_add_f32 v[80:81], v[80:81], v[210:211]
	v_pk_add_f32 v[82:83], v[82:83], v[212:213]
	global_store_dwordx4 v229, v[80:83], s[58:59] offset:0
	s_waitcnt vmcnt(15)
	v_pk_add_f32 v[76:77], v[76:77], v[214:215]
	v_pk_add_f32 v[78:79], v[78:79], v[216:217]
	global_store_dwordx4 v229, v[76:79], s[58:59] offset:64
	s_waitcnt vmcnt(15)
	v_pk_add_f32 v[68:69], v[68:69], v[218:219]
	v_pk_add_f32 v[70:71], v[70:71], v[220:221]
	global_store_dwordx4 v229, v[68:71], s[58:59] offset:512
	s_waitcnt vmcnt(15)
	v_pk_add_f32 v[64:65], v[64:65], v[222:223]
	v_pk_add_f32 v[66:67], v[66:67], v[224:225]
	global_store_dwordx4 v229, v[64:67], s[58:59] offset:576
	global_load_dwordx4 v[160:163], v230, s[26:27] offset:0
	global_load_dwordx4 v[164:167], v230, s[26:27] offset:64
	global_load_dwordx4 v[168:171], v230, s[26:27] offset:512
	global_load_dwordx4 v[172:175], v230, s[26:27] offset:576
	global_load_dwordx4 v[176:179], v231, s[26:27] offset:0
	global_load_dwordx4 v[180:183], v231, s[26:27] offset:64
	global_load_dwordx4 v[184:187], v231, s[26:27] offset:512
	global_load_dwordx4 v[188:191], v231, s[26:27] offset:576
	global_load_dwordx4 v[192:195], v232, s[26:27] offset:0
	global_load_dwordx4 v[196:199], v232, s[26:27] offset:64
	global_load_dwordx4 v[200:203], v232, s[26:27] offset:512
	global_load_dwordx4 v[206:209], v232, s[26:27] offset:576
	global_load_dwordx4 v[210:213], v233, s[26:27] offset:0
	global_load_dwordx4 v[214:217], v233, s[26:27] offset:64
	global_load_dwordx4 v[218:221], v233, s[26:27] offset:512
	global_load_dwordx4 v[222:225], v233, s[26:27] offset:576
	s_waitcnt vmcnt(15)
	v_pk_add_f32 v[60:61], v[60:61], v[160:161]
	v_pk_add_f32 v[62:63], v[62:63], v[162:163]
	global_store_dwordx4 v230, v[60:63], s[58:59] offset:0
	s_waitcnt vmcnt(15)
	v_pk_add_f32 v[56:57], v[56:57], v[164:165]
	v_pk_add_f32 v[58:59], v[58:59], v[166:167]
	global_store_dwordx4 v230, v[56:59], s[58:59] offset:64
	s_waitcnt vmcnt(15)
	v_pk_add_f32 v[52:53], v[52:53], v[168:169]
	v_pk_add_f32 v[54:55], v[54:55], v[170:171]
	global_store_dwordx4 v230, v[52:55], s[58:59] offset:512
	s_waitcnt vmcnt(15)
	v_pk_add_f32 v[40:41], v[40:41], v[172:173]
	v_pk_add_f32 v[42:43], v[42:43], v[174:175]
	global_store_dwordx4 v230, v[40:43], s[58:59] offset:576
	s_waitcnt vmcnt(15)
	v_pk_add_f32 v[48:49], v[48:49], v[176:177]
	v_pk_add_f32 v[50:51], v[50:51], v[178:179]
	global_store_dwordx4 v231, v[48:51], s[58:59] offset:0
	s_waitcnt vmcnt(15)
	v_pk_add_f32 v[44:45], v[44:45], v[180:181]
	v_pk_add_f32 v[46:47], v[46:47], v[182:183]
	global_store_dwordx4 v231, v[44:47], s[58:59] offset:64
	s_waitcnt vmcnt(15)
	v_pk_add_f32 v[36:37], v[36:37], v[184:185]
	v_pk_add_f32 v[38:39], v[38:39], v[186:187]
	global_store_dwordx4 v231, v[36:39], s[58:59] offset:512
	s_waitcnt vmcnt(15)
	v_pk_add_f32 v[24:25], v[24:25], v[188:189]
	v_pk_add_f32 v[26:27], v[26:27], v[190:191]
	global_store_dwordx4 v231, v[24:27], s[58:59] offset:576
	s_waitcnt vmcnt(15)
	v_pk_add_f32 v[32:33], v[32:33], v[192:193]
	v_pk_add_f32 v[34:35], v[34:35], v[194:195]
	global_store_dwordx4 v232, v[32:35], s[58:59] offset:0
	s_waitcnt vmcnt(15)
	v_pk_add_f32 v[28:29], v[28:29], v[196:197]
	v_pk_add_f32 v[30:31], v[30:31], v[198:199]
	global_store_dwordx4 v232, v[28:31], s[58:59] offset:64
	s_waitcnt vmcnt(15)
	v_pk_add_f32 v[20:21], v[20:21], v[200:201]
	v_pk_add_f32 v[22:23], v[22:23], v[202:203]
	global_store_dwordx4 v232, v[20:23], s[58:59] offset:512
	s_waitcnt vmcnt(15)
	v_pk_add_f32 v[8:9], v[8:9], v[206:207]
	v_pk_add_f32 v[10:11], v[10:11], v[208:209]
	global_store_dwordx4 v232, v[8:11], s[58:59] offset:576
	s_waitcnt vmcnt(15)
	v_pk_add_f32 v[16:17], v[16:17], v[210:211]
	v_pk_add_f32 v[18:19], v[18:19], v[212:213]
	global_store_dwordx4 v233, v[16:19], s[58:59] offset:0
	s_waitcnt vmcnt(15)
	v_pk_add_f32 v[12:13], v[12:13], v[214:215]
	v_pk_add_f32 v[14:15], v[14:15], v[216:217]
	global_store_dwordx4 v233, v[12:15], s[58:59] offset:64
	s_waitcnt vmcnt(15)
	v_pk_add_f32 v[4:5], v[4:5], v[218:219]
	v_pk_add_f32 v[6:7], v[6:7], v[220:221]
	global_store_dwordx4 v233, v[4:7], s[58:59] offset:512
	s_waitcnt vmcnt(15)
	v_pk_add_f32 v[0:1], v[0:1], v[222:223]
	v_pk_add_f32 v[2:3], v[2:3], v[224:225]
	global_store_dwordx4 v233, v[0:3], s[58:59] offset:576
	s_cbranch_vccnz .LBB0_764
	s_andn2_b64 vcc, exec, s[12:13]
	s_cbranch_vccnz .LBB0_763
	s_barrier
	s_branch .LBB0_763
